# attention LDS-DMA issue: removed the save/restore of m0 around every global_load_lds (m0 is only ever a DMA destination in this kernel), 2 fewer SALU and no m0 read-back per piece
# speedup vs baseline: 1.0011x; 1.0011x over previous
; template <int DK>
; DI void attn_pass(const AttnSrc& s, const int q0, const float sc, LAS unsigned char* lds, f32x16 (&O)[4]) {
;     ...
;   const int NT = (q0 + 256) / 64;
;   const bf16_t* kp[KP]; int kstr[KP]; const bf16_t* vp[2];
; #pragma unroll
;   for (int i = 0; i < KP; ++i) {
;     const int o = (wid + 8 * i) * 1024 + lane * 16, row = o / ROWB, pc = (o % ROWB) >> 4;
;     const int lc = (DK == 64) ? (pc ^ (row & 7)) : ((pc & ~7) | ((pc & 7) ^ ((row >> 1) & 7)));
;     const int e = lc * 8;
;     if (e < s.nk0) { kp[i] = s.k0 + (size_t)row * s.ldk0 + e; kstr[i] = 64 * s.ldk0; } else { kp[i] = s.k1 + (size_t)row * s.ldk1 + (e - s.nk0); kstr[i] = 64 * s.ldk1; }
;   }
; #pragma unroll
;   for (int i = 0; i < 2; ++i) {
;     const int o = (wid + 8 * i) * 1024 + lane * 16, row = o >> 8, pc = (o >> 4) & 15;
;     const int lc = (((pc >> 2) ^ (row & 3)) << 2) | (pc & 3);
;     vp[i] = s.v + (size_t)row * s.ldv + lc * 8;
;   }
;   const int vstr = 64 * s.ldv;
;   const unsigned lds0 = (unsigned)reinterpret_cast<__UINTPTR_TYPE__>(lds);
;   auto issue = [&](int t, int buf) {
; #pragma unroll
;     for (int i = 0; i < KP; ++i) glds16(kp[i] + (size_t)t * kstr[i], (unsigned)__builtin_amdgcn_readfirstlane(lds0 + buf * STG + (wid + 8 * i) * 1024));
; #pragma unroll
;     for (int i = 0; i < 2; ++i) glds16(vp[i] + (size_t)t * vstr, (unsigned)__builtin_amdgcn_readfirstlane(lds0 + buf * STG + KSZ + (wid + 8 * i) * 1024));
;   };
; #pragma unroll
;   for (int i = 0; i < DPF; ++i) issue(i, i);
;   bf16x8 qf[NS];
; #pragma unroll
;   for (int i = 0; i < NS; ++i) qf[i] = *(const bf16x8*)(s.q + (size_t)(qw0 + r) * s.ldq + 16 * i + 8 * h);
; #pragma unroll
;   for (int i = 0; i < NS; ++i) asm volatile("" : "+v"(qf[i]));
.LBB0_99:
	s_xor_b64 s[10:11], s[12:13], -1
	s_lshl_b64 s[14:15], s[14:15], 1
	v_mov_b32_e32 v24, v163
	s_add_u32 s14, s22, s14
	s_addc_u32 s15, s23, s15
	v_readfirstlane_b32 s18, v24
	s_ashr_i32 s18, s18, 6
	s_lshl_b32 s45, s18, 5
	v_and_b32_e32 v0, 63, v24
	s_lshl_b32 s18, s18, 10
	v_lshl_or_b32 v8, v0, 4, s18
	v_ashrrev_i32_e32 v0, 31, v8
	v_lshrrev_b32_e32 v0, 25, v0
	v_add_u32_e32 v0, v8, v0
	v_ashrrev_i32_e32 v3, 7, v0
	v_and_b32_e32 v0, 0xffffff80, v0
	v_sub_u32_e32 v0, v8, v0
	v_ashrrev_i32_e32 v0, 4, v0
	v_lshrrev_b32_e32 v4, 1, v3
	v_bitop3_b32 v9, v0, v4, 7 bitop3:0x78
	v_lshlrev_b32_e32 v2, 3, v9
	v_mov_b64_e32 v[4:5], s[14:15]
	v_mad_i64_i32 v[6:7], s[14:15], v3, s59, v[4:5]
	v_ashrrev_i32_e32 v3, 31, v2
	v_ashrrev_i32_e32 v0, 8, v8
	v_lshl_add_u64 v[2:3], v[2:3], 1, v[6:7]
	v_lshlrev_b32_e32 v6, 2, v0
	v_and_b32_e32 v10, 3, v24
	v_xor_b32_e32 v6, v6, v24
	v_and_or_b32 v11, v6, 12, v10
	v_mul_hi_i32_i24_e32 v7, 0x1800, v0
	v_mul_i32_i24_e32 v6, 0x1800, v0
	v_lshl_add_u64 v[6:7], s[4:5], 0, v[6:7]
	v_lshlrev_b32_e32 v0, 4, v11
	v_lshl_add_u64 v[18:19], v[6:7], 0, v[0:1]
	v_add_u32_e32 v0, 0x2000, v8
	v_ashrrev_i32_e32 v0, 8, v0
	v_lshlrev_b32_e32 v6, 2, v0
	v_xor_b32_e32 v6, v6, v24
	v_and_or_b32 v8, v6, 12, v10
	v_mul_hi_i32_i24_e32 v7, 0x1800, v0
	v_mul_i32_i24_e32 v6, 0x1800, v0
	v_lshl_add_u64 v[6:7], s[4:5], 0, v[6:7]
	v_lshlrev_b32_e32 v0, 4, v8
	v_cmp_gt_i32_e32 vcc, 8, v9
	v_lshl_add_u64 v[20:21], v[6:7], 0, v[0:1]
	s_waitcnt vmcnt(0)
	s_mov_b64 s[14:15], 0x800
	v_cndmask_b32_e64 v7, -1, 0, vcc
	v_cndmask_b32_e64 v6, v200, 0, vcc
	v_lshl_add_u64 v[22:23], v[2:3], 0, v[6:7]
	v_lshl_add_u64 v[2:3], v[22:23], 0, s[14:15]
	s_add_i32 s46, s18, 0
	s_mov_b32 m0, s46
	s_nop 0
	global_load_lds_dwordx4 v[2:3], off
	s_add_i32 s47, s46, 0x2000
	s_mov_b32 m0, s47
	s_nop 0
	global_load_lds_dwordx4 v[18:19], off
	s_add_i32 s52, s46, 0x4000
	s_mov_b32 m0, s52
	s_nop 0
	global_load_lds_dwordx4 v[20:21], off
	s_mov_b64 s[14:15], 0x60800
	v_lshl_add_u64 v[2:3], v[22:23], 0, s[14:15]
	s_add_i32 s14, s46, 0x6000
	s_mov_b32 m0, s14
	s_nop 0
	global_load_lds_dwordx4 v[2:3], off
	v_lshl_add_u64 v[2:3], v[18:19], 0, s[26:27]
	s_add_i32 s14, s46, 0x8000
	s_mov_b32 m0, s14
	s_nop 0
	global_load_lds_dwordx4 v[2:3], off
	v_lshl_add_u64 v[2:3], v[20:21], 0, s[26:27]
	s_add_i32 s14, s46, 0xa000
	s_mov_b32 m0, s14
	s_nop 0
	global_load_lds_dwordx4 v[2:3], off
	s_mov_b64 s[14:15], 0xc0800
	v_lshl_add_u64 v[2:3], v[22:23], 0, s[14:15]
	s_add_i32 s14, s46, 0xc000
	v_and_b32_e32 v25, 31, v24
	s_add_i32 s45, s45, s40
	s_mov_b32 m0, s14
	s_nop 0
	global_load_lds_dwordx4 v[2:3], off
	v_lshl_add_u64 v[2:3], v[18:19], 0, s[28:29]
	s_add_i32 s14, s46, 0xe000
	v_bfe_u32 v26, v24, 5, 1
	s_mov_b32 m0, s14
	s_nop 0
	global_load_lds_dwordx4 v[2:3], off
	v_lshl_add_u64 v[2:3], v[20:21], 0, s[28:29]
	s_add_i32 s14, s46, 0x10000
	v_or_b32_e32 v212, s45, v25
	s_mov_b32 m0, s14
	s_nop 0
	global_load_lds_dwordx4 v[2:3], off
	v_lshlrev_b32_e32 v0, 4, v26
	v_mad_i64_i32 v[2:3], s[14:15], v212, s59, v[4:5]
	v_lshl_add_u64 v[14:15], v[2:3], 0, v[0:1]
	global_load_dwordx4 v[2:5], v[14:15], off
	global_load_dwordx4 v[6:9], v[14:15], off offset:32
	global_load_dwordx4 v[10:13], v[14:15], off offset:64
	s_nop 0
	global_load_dwordx4 v[14:17], v[14:15], off offset:96
	s_mov_b64 s[14:15], 0x120800
	v_lshlrev_b32_e32 v213, 7, v25
	v_lshlrev_b32_e32 v214, 10, v26
	v_lshlrev_b32_e32 v223, 2, v26
	v_lshl_add_u64 v[166:167], v[20:21], 0, s[30:31]
	v_lshl_add_u64 v[168:169], v[18:19], 0, s[30:31]
	v_lshl_add_u64 v[170:171], v[22:23], 0, s[14:15]
	s_mov_b32 s53, 63
	s_mov_b32 s54, 3
	s_mov_b32 s55, 0
	s_or_b32 s56, s45, 31
	v_mov_b32_e32 v227, 0
	s_mov_b32 s57, s44
	s_mov_b64 s[14:15], 0
	s_mov_b32 s58, 3
	s_waitcnt vmcnt(3)
	s_nop 0
	v_lshlrev_b32_e32 v0, 16, v2
	v_and_b32_e32 v2, 0xffff0000, v2
	v_mul_f32_e32 v2, 0x3e38aa3b, v2
	s_waitcnt vmcnt(2)
	s_waitcnt vmcnt(1)
	s_waitcnt vmcnt(0)
; DI unsigned cvt_pk_bf16(float lo, float hi) { unsigned r; asm volatile("v_cvt_pk_bf16_f32 %0, %1, %2" : "=v"(r) : "v"(lo), "v"(hi)); return r; }
; DI float bf_lo(unsigned w) { return __uint_as_float(w << 16); }
; DI float bf_hi(unsigned w) { return __uint_as_float(w & 0xffff0000u); }
; template <int DK>
; DI void attn_pass(const AttnSrc& s, const int q0, const float sc, LAS unsigned char* lds, f32x16 (&O)[4]) {
;     ...
;   if (REL) {
; #pragma unroll
;   for (int i = 0; i < NS; ++i) {
;     const u32x4 w = __builtin_bit_cast(u32x4, qf[i]); u32x4 o;
;     o.x = cvt_pk_bf16(bf_lo(w.x) * sc, bf_hi(w.x) * sc); o.y = cvt_pk_bf16(bf_lo(w.y) * sc, bf_hi(w.y) * sc);
;     o.z = cvt_pk_bf16(bf_lo(w.z) * sc, bf_hi(w.z) * sc); o.w = cvt_pk_bf16(bf_lo(w.w) * sc, bf_hi(w.w) * sc);
;     qf[i] = __builtin_bit_cast(bf16x8, o);
;   }
;   }
;   f32x16 negm;
; #pragma unroll
;   for (int j = 0; j < 16; ++j) negm[j] = 0.f;
;   if (REL) asm volatile("" : "+v"(negm));
;   const int kx = (DK == 64) ? (r & 7) : ((r >> 1) & 7);
;   const int krow = r * ROWB;
;   const int i15 = lane & 15;
;   const int vrow = (4 * h + (i15 >> 2)) * 256 + ((lane >> 4) & 1) * 32 + (lane & 3) * 8;
;   const int vx = (i15 >> 2) & 3;
;   int buf = 0, pbuf = DPF;
	v_lshlrev_b32_e32 v29, 16, v5
	v_mul_f32_e32 v0, 0x3e38aa3b, v0
	v_cvt_pk_bf16_f32 v128, v0, v2
	v_and_b32_e32 v2, 0xffff0000, v5
	v_lshlrev_b32_e32 v27, 16, v3
	v_and_b32_e32 v3, 0xffff0000, v3
	v_lshlrev_b32_e32 v28, 16, v4
	v_and_b32_e32 v4, 0xffff0000, v4
	v_mul_f32_e32 v0, 0x3e38aa3b, v29
	v_mul_f32_e32 v2, 0x3e38aa3b, v2
	v_mul_f32_e32 v27, 0x3e38aa3b, v27
	v_mul_f32_e32 v3, 0x3e38aa3b, v3
	v_mul_f32_e32 v28, 0x3e38aa3b, v28
	v_mul_f32_e32 v4, 0x3e38aa3b, v4
	v_cvt_pk_bf16_f32 v129, v27, v3
	v_cvt_pk_bf16_f32 v130, v28, v4
	v_cvt_pk_bf16_f32 v131, v0, v2
	v_lshlrev_b32_e32 v0, 16, v6
	v_and_b32_e32 v2, 0xffff0000, v6
	v_mul_f32_e32 v0, 0x3e38aa3b, v0
	v_mul_f32_e32 v2, 0x3e38aa3b, v2
	v_cvt_pk_bf16_f32 v132, v0, v2
	v_lshlrev_b32_e32 v0, 16, v7
	v_and_b32_e32 v2, 0xffff0000, v7
	v_mul_f32_e32 v0, 0x3e38aa3b, v0
	v_mul_f32_e32 v2, 0x3e38aa3b, v2
	v_cvt_pk_bf16_f32 v133, v0, v2
	v_lshlrev_b32_e32 v0, 16, v8
	v_and_b32_e32 v2, 0xffff0000, v8
	v_mul_f32_e32 v0, 0x3e38aa3b, v0
	v_mul_f32_e32 v2, 0x3e38aa3b, v2
	v_cvt_pk_bf16_f32 v134, v0, v2
	v_lshlrev_b32_e32 v0, 16, v9
	v_and_b32_e32 v2, 0xffff0000, v9
	v_mul_f32_e32 v0, 0x3e38aa3b, v0
	v_mul_f32_e32 v2, 0x3e38aa3b, v2
	v_cvt_pk_bf16_f32 v135, v0, v2
	v_lshlrev_b32_e32 v0, 16, v10
	v_and_b32_e32 v2, 0xffff0000, v10
	v_mul_f32_e32 v0, 0x3e38aa3b, v0
	v_mul_f32_e32 v2, 0x3e38aa3b, v2
	v_cvt_pk_bf16_f32 v136, v0, v2
	v_lshlrev_b32_e32 v0, 16, v11
	v_and_b32_e32 v2, 0xffff0000, v11
	v_mul_f32_e32 v0, 0x3e38aa3b, v0
	v_mul_f32_e32 v2, 0x3e38aa3b, v2
	v_cvt_pk_bf16_f32 v137, v0, v2
	v_lshlrev_b32_e32 v0, 16, v12
	v_and_b32_e32 v2, 0xffff0000, v12
	v_mul_f32_e32 v0, 0x3e38aa3b, v0
	v_mul_f32_e32 v2, 0x3e38aa3b, v2
	v_cvt_pk_bf16_f32 v138, v0, v2
	v_lshlrev_b32_e32 v0, 16, v13
	v_and_b32_e32 v2, 0xffff0000, v13
	v_mul_f32_e32 v0, 0x3e38aa3b, v0
	v_mul_f32_e32 v2, 0x3e38aa3b, v2
	v_cvt_pk_bf16_f32 v139, v0, v2
	v_lshlrev_b32_e32 v0, 16, v14
	v_and_b32_e32 v2, 0xffff0000, v14
	v_mul_f32_e32 v0, 0x3e38aa3b, v0
	v_mul_f32_e32 v2, 0x3e38aa3b, v2
	v_cvt_pk_bf16_f32 v140, v0, v2
	v_lshlrev_b32_e32 v0, 16, v15
	v_and_b32_e32 v2, 0xffff0000, v15
	v_mul_f32_e32 v0, 0x3e38aa3b, v0
	v_mul_f32_e32 v2, 0x3e38aa3b, v2
	v_cvt_pk_bf16_f32 v141, v0, v2
	v_lshlrev_b32_e32 v0, 16, v16
	v_and_b32_e32 v2, 0xffff0000, v16
	v_mul_f32_e32 v0, 0x3e38aa3b, v0
	v_mul_f32_e32 v2, 0x3e38aa3b, v2
	v_cvt_pk_bf16_f32 v142, v0, v2
	v_lshlrev_b32_e32 v0, 16, v17
	v_and_b32_e32 v2, 0xffff0000, v17
	v_lshlrev_b32_e32 v17, 1, v24
	v_and_b32_e32 v216, 32, v17
	v_lshlrev_b32_e32 v17, 3, v24
	v_bfe_u32 v16, v24, 2, 2
	v_and_b32_e32 v217, 24, v17
	v_bfe_u32 v17, v24, 1, 3
	v_bitop3_b32 v24, v26, v17, 7 bitop3:0x78
	v_lshlrev_b32_e32 v218, 4, v24
	v_bitop3_b32 v24, v26, v17, 2 bitop3:0x36
	v_mul_f32_e32 v0, 0x3e38aa3b, v0
	v_mul_f32_e32 v2, 0x3e38aa3b, v2
	v_mov_b32_e32 v14, v1
	v_mov_b32_e32 v15, v1
	v_lshlrev_b32_e32 v219, 4, v24
	v_bitop3_b32 v24, v26, v17, 4 bitop3:0x36
	v_bitop3_b32 v17, v26, v17, 6 bitop3:0x36
	v_cvt_pk_bf16_f32 v143, v0, v2
	v_mov_b32_e32 v0, v1
	v_mov_b32_e32 v2, v1
	v_mov_b32_e32 v3, v1
	v_mov_b32_e32 v4, v1
	v_mov_b32_e32 v5, v1
	v_mov_b32_e32 v6, v1
	v_mov_b32_e32 v7, v1
	v_mov_b32_e32 v8, v1
	v_mov_b32_e32 v9, v1
	v_mov_b32_e32 v10, v1
	v_mov_b32_e32 v11, v1
	v_mov_b32_e32 v12, v1
	v_mov_b32_e32 v13, v1
	v_mov_b64_e32 v[94:95], v[14:15]
	v_lshlrev_b32_e32 v215, 8, v16
	v_lshlrev_b32_e32 v220, 4, v24
	v_lshlrev_b32_e32 v221, 4, v17
	v_lshlrev_b32_e32 v222, 6, v16
	v_mov_b64_e32 v[30:31], v[14:15]
	v_mov_b64_e32 v[46:47], v[14:15]
	v_mov_b64_e32 v[62:63], v[14:15]
	v_mov_b64_e32 v[78:79], v[14:15]
	v_mov_b64_e32 v[92:93], v[12:13]
	v_mov_b64_e32 v[90:91], v[10:11]
	v_mov_b64_e32 v[88:89], v[8:9]
	v_mov_b64_e32 v[86:87], v[6:7]
	v_mov_b64_e32 v[84:85], v[4:5]
	v_mov_b64_e32 v[82:83], v[2:3]
	v_mov_b64_e32 v[80:81], v[0:1]
	v_xor_b32_e32 v224, 64, v222
	v_xor_b32_e32 v225, 0x80, v222
	v_xor_b32_e32 v226, 0xc0, v222
	v_mov_b64_e32 v[28:29], v[12:13]
	v_mov_b64_e32 v[26:27], v[10:11]
	v_mov_b64_e32 v[24:25], v[8:9]
	v_mov_b64_e32 v[22:23], v[6:7]
	v_mov_b64_e32 v[20:21], v[4:5]
	v_mov_b64_e32 v[18:19], v[2:3]
	v_mov_b64_e32 v[16:17], v[0:1]
	v_mov_b64_e32 v[44:45], v[12:13]
	v_mov_b64_e32 v[42:43], v[10:11]
	v_mov_b64_e32 v[40:41], v[8:9]
	v_mov_b64_e32 v[38:39], v[6:7]
	v_mov_b64_e32 v[36:37], v[4:5]
	v_mov_b64_e32 v[34:35], v[2:3]
	v_mov_b64_e32 v[32:33], v[0:1]
	v_mov_b64_e32 v[60:61], v[12:13]
	v_mov_b64_e32 v[58:59], v[10:11]
	v_mov_b64_e32 v[56:57], v[8:9]
	v_mov_b64_e32 v[54:55], v[6:7]
	v_mov_b64_e32 v[52:53], v[4:5]
	v_mov_b64_e32 v[50:51], v[2:3]
	v_mov_b64_e32 v[48:49], v[0:1]
	v_mov_b64_e32 v[76:77], v[12:13]
	v_mov_b64_e32 v[74:75], v[10:11]
	v_mov_b64_e32 v[72:73], v[8:9]
	v_mov_b64_e32 v[70:71], v[6:7]
	v_mov_b64_e32 v[68:69], v[4:5]
	v_mov_b64_e32 v[66:67], v[2:3]
	v_mov_b64_e32 v[64:65], v[0:1]
	v_mov_b32_e32 v14, 0
	s_branch .LBB0_102

; #define LAS __attribute__((address_space(3)))
; template <int DK>
; DI void attn_pass(const AttnSrc& s, const int q0, const float sc, LAS unsigned char* lds, f32x16 (&O)[4]) {
;     ...
;     if (t + DPF < NT) issue(t + DPF, pbuf);
;     if (64 * t <= qw0 + 31) {
;       LAS unsigned char* Kb = lds + buf * STG; LAS unsigned char* Vb = lds + buf * STG + KSZ;
;       f32x16 p0, p1;
;       constexpr int GS = (DK == 64) ? 4 : 2, NG = NS / GS;
;       bf16x8 kfa[2][GS], kfb[2][GS];
;       auto kload = [&](int g, int slot) {
; #pragma unroll
;         for (int j = 0; j < GS; ++j) { const int lc = 2 * (g * GS + j) + h; const int ph = (DK == 64) ? (lc ^ kx) : ((lc & ~7) | ((lc & 7) ^ kx));
;           kfa[slot][j] = *(const LAS bf16x8*)(Kb + krow + ph * 16); kfb[slot][j] = *(const LAS bf16x8*)(Kb + krow + 32 * ROWB + ph * 16); }
;       };
;       kload(0, 0);
; #pragma unroll
;       for (int g = 0; g < NG; ++g) {
;         if (g + 1 < NG) kload(g + 1, (g + 1) & 1);
;         __builtin_amdgcn_s_setprio(1);
; #pragma unroll
;         for (int j = 0; j < GS; ++j) {
;           if (g == 0 && j == 0) {
;             if (REL) {
;               p0 = __builtin_amdgcn_mfma_f32_32x32x16_bf16(kfa[0][0], qf[0], negm, 0, 0, 0);
;               p1 = __builtin_amdgcn_mfma_f32_32x32x16_bf16(kfb[0][0], qf[0], negm, 0, 0, 0);
;             } else {
;               f32x16 z;
; #pragma unroll
;               for (int jj = 0; jj < 16; ++jj) z[jj] = 0.f;
;               p0 = __builtin_amdgcn_mfma_f32_32x32x16_bf16(kfa[0][0], qf[0], z, 0, 0, 0);
;               p1 = __builtin_amdgcn_mfma_f32_32x32x16_bf16(kfb[0][0], qf[0], z, 0, 0, 0);
;             }
;           } else {
;             p0 = __builtin_amdgcn_mfma_f32_32x32x16_bf16(kfa[g & 1][j], qf[g * GS + j], p0, 0, 0, 0);
;             p1 = __builtin_amdgcn_mfma_f32_32x32x16_bf16(kfb[g & 1][j], qf[g * GS + j], p1, 0, 0, 0);
;           }
;         }
;         __builtin_amdgcn_s_setprio(0);
;       }
.LBB0_112:
	s_sub_i32 s18, s53, 63
	s_cmp_gt_i32 s18, s56
	s_cbranch_scc1 .Ln64_skip
	s_mul_i32 s18, s55, 0x6000
	s_add_i32 s18, s18, 0
	v_add_u32_e32 v0, s18, v213
	v_add_u32_e32 v6, v0, v218
	v_add_u32_e32 v15, v0, v219
	ds_read_b128 v[2:5], v6
	ds_read_b128 v[6:9], v6 offset:4096
	ds_read_b128 v[10:13], v15
	ds_read_b128 v[144:147], v15 offset:4096
	v_add_u32_e32 v15, v0, v220
	v_add_u32_e32 v0, v0, v221
	ds_read_b128 v[230:233], v15
	ds_read_b128 v[234:237], v15 offset:4096
	ds_read_b128 v[238:241], v0
	ds_read_b128 v[242:245], v0 offset:4096
	s_setprio 1
	s_waitcnt lgkmcnt(6)
	v_mfma_f32_32x32x16_bf16 v[112:127], v[2:5], v[128:131], v[80:95]
	v_mfma_f32_32x32x16_bf16 v[96:111], v[6:9], v[128:131], v[80:95]
	s_waitcnt lgkmcnt(4)
	v_mfma_f32_32x32x16_bf16 v[112:127], v[10:13], v[132:135], v[112:127]
	v_mfma_f32_32x32x16_bf16 v[96:111], v[144:147], v[132:135], v[96:111]
	s_waitcnt lgkmcnt(2)
	v_mfma_f32_32x32x16_bf16 v[112:127], v[230:233], v[136:139], v[112:127]
	v_mfma_f32_32x32x16_bf16 v[96:111], v[234:237], v[136:139], v[96:111]
	s_waitcnt lgkmcnt(0)
	v_mfma_f32_32x32x16_bf16 v[112:127], v[238:241], v[140:143], v[112:127]
	v_mfma_f32_32x32x16_bf16 v[96:111], v[242:245], v[140:143], v[96:111]
	s_setprio 0
	v_add3_u32 v0, s18, v214, v215
	v_add3_u32 v15, v0, v216, v217
	v_add_u32_e32 v246, v15, v222
	v_add_u32_e32 v247, v15, v224
	v_add_u32_e32 v248, v15, v225
	v_add_u32_e32 v249, v15, v226
	s_cmp_ge_u32 s54, s41
	s_cbranch_scc1 .Ln64_dmadone
	s_mul_i32 s18, s58, 0x6000
	v_lshl_add_u64 v[2:3], v[170:171], 0, s[14:15]
	s_add_i32 s19, s18, s46
	s_mov_b32 m0, s19
	s_nop 0
	global_load_lds_dwordx4 v[2:3], off
	v_lshl_add_u64 v[2:3], v[168:169], 0, s[14:15]
	s_add_i32 s19, s18, s47
	s_mov_b32 m0, s19
	s_nop 0
	global_load_lds_dwordx4 v[2:3], off
	v_lshl_add_u64 v[2:3], v[166:167], 0, s[14:15]
	s_add_i32 s18, s18, s52
	s_mov_b32 m0, s18
	s_nop 0
	global_load_lds_dwordx4 v[2:3], off

; template <int DK>
; DI void attn_pass(const AttnSrc& s, const int q0, const float sc, LAS unsigned char* lds, f32x16 (&O)[4]) {
;     ...
;   auto issue = [&](int t, int buf) {
; #pragma unroll
;     for (int i = 0; i < KP; ++i) glds16(kp[i] + (size_t)t * kstr[i], (unsigned)__builtin_amdgcn_readfirstlane(lds0 + buf * STG + (wid + 8 * i) * 1024));
; #pragma unroll
;     for (int i = 0; i < 2; ++i) glds16(vp[i] + (size_t)t * vstr, (unsigned)__builtin_amdgcn_readfirstlane(lds0 + buf * STG + KSZ + (wid + 8 * i) * 1024));
;   };
;     ...
;     if (t + DPF < NT) issue(t + DPF, pbuf);
.Ln64_skip:
	s_cmp_ge_u32 s54, s41
	s_cbranch_scc1 .LBB0_101
	s_mul_i32 s18, s58, 0x6000
	v_lshl_add_u64 v[2:3], v[170:171], 0, s[14:15]
	s_add_i32 s19, s18, s46
	s_mov_b32 m0, s19
	s_nop 0
	global_load_lds_dwordx4 v[2:3], off
	v_lshl_add_u64 v[2:3], v[168:169], 0, s[14:15]
	s_add_i32 s19, s18, s47
	s_mov_b32 m0, s19
	s_nop 0
	global_load_lds_dwordx4 v[2:3], off
	v_lshl_add_u64 v[2:3], v[166:167], 0, s[14:15]
	s_add_i32 s18, s18, s52
	s_mov_b32 m0, s18
	s_nop 0
	global_load_lds_dwordx4 v[2:3], off
	s_branch .LBB0_101

; template <int DK>
; DI void attn_pass(const AttnSrc& s, const int q0, const float sc, LAS unsigned char* lds, f32x16 (&O)[4]) {
;     ...
;   const bf16_t* kp[KP]; int kstr[KP]; const bf16_t* vp[2];
; #pragma unroll
;   for (int i = 0; i < KP; ++i) {
;     const int o = (wid + 8 * i) * 1024 + lane * 16, row = o / ROWB, pc = (o % ROWB) >> 4;
;     const int lc = (DK == 64) ? (pc ^ (row & 7)) : ((pc & ~7) | ((pc & 7) ^ ((row >> 1) & 7)));
;     const int e = lc * 8;
;     if (e < s.nk0) { kp[i] = s.k0 + (size_t)row * s.ldk0 + e; kstr[i] = 64 * s.ldk0; } else { kp[i] = s.k1 + (size_t)row * s.ldk1 + (e - s.nk0); kstr[i] = 64 * s.ldk1; }
;   }
; #pragma unroll
;   for (int i = 0; i < 2; ++i) {
;     const int o = (wid + 8 * i) * 1024 + lane * 16, row = o >> 8, pc = (o >> 4) & 15;
;     const int lc = (((pc >> 2) ^ (row & 3)) << 2) | (pc & 3);
;     vp[i] = s.v + (size_t)row * s.ldv + lc * 8;
;   }
;   const int vstr = 64 * s.ldv;
;   const unsigned lds0 = (unsigned)reinterpret_cast<__UINTPTR_TYPE__>(lds);
;   auto issue = [&](int t, int buf) {
; #pragma unroll
;     for (int i = 0; i < KP; ++i) glds16(kp[i] + (size_t)t * kstr[i], (unsigned)__builtin_amdgcn_readfirstlane(lds0 + buf * STG + (wid + 8 * i) * 1024));
; #pragma unroll
;     for (int i = 0; i < 2; ++i) glds16(vp[i] + (size_t)t * vstr, (unsigned)__builtin_amdgcn_readfirstlane(lds0 + buf * STG + KSZ + (wid + 8 * i) * 1024));
;   };
; #pragma unroll
;   for (int i = 0; i < DPF; ++i) issue(i, i);
.LBB0_123:
	v_mov_b32_e32 v16, v163
	s_waitcnt vmcnt(0)
	s_nop 0
	v_readfirstlane_b32 s12, v16
	s_ashr_i32 s40, s12, 6
	v_and_b32_e32 v18, 63, v16
	s_lshl_b32 s41, s40, 10
	v_lshl_or_b32 v17, v18, 4, s41
	v_mul_hi_i32 v0, v17, s60
	v_lshrrev_b32_e32 v2, 31, v0
	v_ashrrev_i32_e32 v0, 6, v0
	v_add_u32_e32 v8, v0, v2
	v_mul_i32_i24_e32 v0, 0x180, v8
	v_sub_u32_e32 v0, v17, v0
	v_ashrrev_i32_e32 v0, 4, v0
	v_lshrrev_b32_e32 v2, 1, v8
	v_bitop3_b32 v0, v2, v0, 7 bitop3:0x6c
	v_lshlrev_b32_e32 v6, 3, v0
	v_cmp_lt_i32_e32 vcc, 15, v0
	v_ashrrev_i32_e32 v9, 31, v8
	s_and_saveexec_b64 s[12:13], vcc
	s_xor_b64 s[12:13], exec, s[12:13]
	v_mul_hi_i32_i24_e32 v3, 0xc00, v8
	v_mul_i32_i24_e32 v2, 0xc00, v8
	v_lshl_add_u64 v[2:3], s[8:9], 0, v[2:3]
	v_mov_b32_e32 v7, v1
	v_lshl_add_u64 v[2:3], v[6:7], 1, v[2:3]
	v_lshl_add_u64 v[2:3], v[2:3], 0, s[34:35]
	s_or_saveexec_b64 s[12:13], s[12:13]
	v_mov_b64_e32 v[4:5], 0x18000
	s_xor_b64 exec, exec, s[12:13]
	v_lshlrev_b64 v[2:3], 12, v[8:9]
	v_lshl_add_u64 v[2:3], s[6:7], 0, v[2:3]
	v_ashrrev_i32_e32 v7, 31, v6
	v_lshl_add_u64 v[2:3], v[6:7], 1, v[2:3]
	v_mov_b64_e32 v[4:5], 0x20000
	s_or_b64 exec, exec, s[12:13]
	v_add_u32_e32 v5, 0x2000, v17
	v_mul_hi_i32 v0, v5, s60
	v_lshrrev_b32_e32 v6, 31, v0
	v_ashrrev_i32_e32 v0, 6, v0
	v_add_u32_e32 v10, v0, v6
	v_mul_i32_i24_e32 v0, 0x180, v10
	v_sub_u32_e32 v0, v5, v0
	v_ashrrev_i32_e32 v0, 4, v0
	v_lshrrev_b32_e32 v6, 1, v10
	v_bitop3_b32 v6, v6, v0, 7 bitop3:0x6c
	v_lshlrev_b32_e32 v0, 3, v6
	v_cmp_lt_i32_e32 vcc, 15, v6
	v_ashrrev_i32_e32 v11, 31, v10
	s_and_saveexec_b64 s[12:13], vcc
	s_xor_b64 s[12:13], exec, s[12:13]
	v_mul_hi_i32_i24_e32 v7, 0xc00, v10
	v_mul_i32_i24_e32 v6, 0xc00, v10
	v_lshl_add_u64 v[6:7], s[8:9], 0, v[6:7]
	v_lshl_add_u64 v[6:7], v[0:1], 1, v[6:7]
	v_lshl_add_u64 v[6:7], v[6:7], 0, s[34:35]
	s_or_saveexec_b64 s[12:13], s[12:13]
	v_mov_b64_e32 v[8:9], 0x18000
	s_xor_b64 exec, exec, s[12:13]
	v_lshlrev_b64 v[6:7], 12, v[10:11]
	v_lshl_add_u64 v[6:7], s[6:7], 0, v[6:7]
	v_ashrrev_i32_e32 v9, 31, v0
	v_mov_b32_e32 v8, v0
	v_lshl_add_u64 v[6:7], v[8:9], 1, v[6:7]
	v_mov_b64_e32 v[8:9], 0x20000
	s_or_b64 exec, exec, s[12:13]
	v_add_u32_e32 v0, 0x4000, v17
	v_mul_hi_i32 v9, v0, s60
	v_lshrrev_b32_e32 v10, 31, v9
	v_ashrrev_i32_e32 v9, 6, v9
	v_add_u32_e32 v14, v9, v10
	v_mul_i32_i24_e32 v9, 0x180, v14
	v_sub_u32_e32 v0, v0, v9
	v_ashrrev_i32_e32 v0, 4, v0
	v_lshrrev_b32_e32 v9, 1, v14
	v_bitop3_b32 v9, v9, v0, 7 bitop3:0x6c
	v_lshlrev_b32_e32 v0, 3, v9
	v_cmp_lt_i32_e32 vcc, 15, v9
	v_ashrrev_i32_e32 v15, 31, v14
	s_and_saveexec_b64 s[12:13], vcc
	s_xor_b64 s[12:13], exec, s[12:13]
	v_mul_hi_i32_i24_e32 v11, 0xc00, v14
	v_mul_i32_i24_e32 v10, 0xc00, v14
	v_lshl_add_u64 v[10:11], s[8:9], 0, v[10:11]
	v_lshl_add_u64 v[10:11], v[0:1], 1, v[10:11]
	v_lshl_add_u64 v[10:11], v[10:11], 0, s[34:35]
	s_or_saveexec_b64 s[12:13], s[12:13]
	v_mov_b64_e32 v[12:13], 0x18000
	s_xor_b64 exec, exec, s[12:13]
	v_lshlrev_b64 v[10:11], 12, v[14:15]
	v_lshl_add_u64 v[10:11], s[6:7], 0, v[10:11]
	v_ashrrev_i32_e32 v13, 31, v0
	v_mov_b32_e32 v12, v0
	v_lshl_add_u64 v[10:11], v[12:13], 1, v[10:11]
	v_mov_b64_e32 v[12:13], 0x20000
	s_or_b64 exec, exec, s[12:13]
	v_ashrrev_i32_e32 v14, 8, v17
	v_lshlrev_b32_e32 v0, 2, v14
	v_and_b32_e32 v21, 3, v16
	v_xor_b32_e32 v0, v0, v16
	v_ashrrev_i32_e32 v15, 31, v14
	v_and_or_b32 v0, v0, 12, v21
	v_lshlrev_b64 v[14:15], 12, v[14:15]
	v_lshl_add_u64 v[14:15], s[6:7], 0, v[14:15]
	v_lshlrev_b32_e32 v0, 4, v0
	v_ashrrev_i32_e32 v20, 8, v5
	s_xor_b64 s[12:13], s[14:15], -1
	v_lshl_add_u64 v[14:15], v[14:15], 0, v[0:1]
	v_lshlrev_b32_e32 v0, 2, v20
	s_and_b64 s[14:15], s[14:15], exec
	v_xor_b32_e32 v0, v0, v16
	s_cselect_b32 s33, s22, s23
	v_and_or_b32 v0, v0, 12, v21
	v_ashrrev_i32_e32 v21, 31, v20
	s_add_i32 s41, s41, 0
	s_mov_b32 m0, s41
	s_nop 0
	global_load_lds_dwordx4 v[2:3], off
	v_lshlrev_b64 v[20:21], 12, v[20:21]
	s_add_i32 s42, s41, 0x2000
	s_mov_b32 m0, s42
	s_nop 0
	global_load_lds_dwordx4 v[6:7], off
	v_lshl_add_u64 v[20:21], s[6:7], 0, v[20:21]
	v_lshlrev_b32_e32 v0, 4, v0
	s_add_i32 s43, s41, 0x4000
	s_mov_b32 m0, s43
	s_nop 0
	global_load_lds_dwordx4 v[10:11], off
	v_lshrrev_b32_e32 v13, 5, v18
	v_lshl_add_u64 v[18:19], v[14:15], 0, s[36:37]
	v_lshl_add_u64 v[20:21], v[20:21], 0, v[0:1]
	s_add_i32 s44, s41, 0x6000
	s_mov_b32 m0, s44
	s_nop 0
	global_load_lds_dwordx4 v[18:19], off
	v_lshlrev_b32_e32 v170, 1, v4
	v_mov_b32_e32 v171, v1
	v_lshl_add_u64 v[22:23], v[20:21], 0, s[36:37]
	s_add_i32 s45, s41, 0x8000
	s_mov_b32 m0, s45
	s_nop 0
	global_load_lds_dwordx4 v[22:23], off
	v_lshl_add_u64 v[18:19], v[2:3], 0, v[170:171]
	v_lshlrev_b32_e32 v172, 1, v8
; DI unsigned cvt_pk_bf16(float lo, float hi) { unsigned r; asm volatile("v_cvt_pk_bf16_f32 %0, %1, %2" : "=v"(r) : "v"(lo), "v"(hi)); return r; }
; DI float bf_lo(unsigned w) { return __uint_as_float(w << 16); }
; DI float bf_hi(unsigned w) { return __uint_as_float(w & 0xffff0000u); }
; template <int DK>
; DI void attn_pass(const AttnSrc& s, const int q0, const float sc, LAS unsigned char* lds, f32x16 (&O)[4]) {
;     ...
;   for (int i = 0; i < DPF; ++i) issue(i, i);
;   bf16x8 qf[NS];
; #pragma unroll
;   for (int i = 0; i < NS; ++i) qf[i] = *(const bf16x8*)(s.q + (size_t)(qw0 + r) * s.ldq + 16 * i + 8 * h);
; #pragma unroll
;   for (int i = 0; i < NS; ++i) asm volatile("" : "+v"(qf[i]));
;   constexpr bool REL = (DK == 64);
;   if (REL) {
; #pragma unroll
;   for (int i = 0; i < NS; ++i) {
;     const u32x4 w = __builtin_bit_cast(u32x4, qf[i]); u32x4 o;
;     o.x = cvt_pk_bf16(bf_lo(w.x) * sc, bf_hi(w.x) * sc); o.y = cvt_pk_bf16(bf_lo(w.y) * sc, bf_hi(w.y) * sc);
;     o.z = cvt_pk_bf16(bf_lo(w.z) * sc, bf_hi(w.z) * sc); o.w = cvt_pk_bf16(bf_lo(w.w) * sc, bf_hi(w.w) * sc);
;     qf[i] = __builtin_bit_cast(bf16x8, o);
;   }
;   }
;   f32x16 negm;
; #pragma unroll
;   for (int j = 0; j < 16; ++j) negm[j] = 0.f;
;   if (REL) asm volatile("" : "+v"(negm));
;   const int kx = (DK == 64) ? (r & 7) : ((r >> 1) & 7);
;   const int krow = r * ROWB;
;   const int i15 = lane & 15;
;   const int vrow = (4 * h + (i15 >> 2)) * 256 + ((lane >> 4) & 1) * 32 + (lane & 3) * 8;
;   const int vx = (i15 >> 2) & 3;
;   int buf = 0, pbuf = DPF;
	v_mov_b32_e32 v173, v1
	s_add_i32 s14, s41, 0xa000
	s_mov_b32 m0, s14
	s_nop 0
	global_load_lds_dwordx4 v[18:19], off
	v_lshl_add_u64 v[18:19], v[6:7], 0, v[172:173]
	v_lshlrev_b32_e32 v174, 1, v12
	v_mov_b32_e32 v175, v1
	s_add_i32 s14, s41, 0xc000
	s_mov_b32 m0, s14
	s_nop 0
	global_load_lds_dwordx4 v[18:19], off
	v_lshl_add_u64 v[18:19], v[10:11], 0, v[174:175]
	s_lshl_b32 s40, s40, 5
	s_add_i32 s14, s41, 0xe000
	s_mov_b32 m0, s14
	s_nop 0
	global_load_lds_dwordx4 v[18:19], off
	v_lshl_add_u64 v[18:19], v[14:15], 0, s[90:91]
	v_and_b32_e32 v9, 31, v16
	s_add_i32 s40, s40, s33
	s_add_i32 s14, s41, 0x10000
	s_mov_b32 m0, s14
	s_nop 0
	global_load_lds_dwordx4 v[18:19], off
	v_lshl_add_u64 v[18:19], v[20:21], 0, s[90:91]
	s_add_i32 s14, s41, 0x12000
	s_mov_b32 m0, s14
	s_nop 0
	global_load_lds_dwordx4 v[18:19], off
	v_or_b32_e32 v167, s40, v9
	v_mov_b64_e32 v[18:19], s[4:5]
	v_mad_i64_i32 v[18:19], s[14:15], v167, s88, v[18:19]
	v_lshlrev_b32_e32 v0, 4, v13
	v_lshl_add_u64 v[18:19], v[18:19], 0, v[0:1]
	global_load_dwordx4 v[98:101], v[18:19], off
	global_load_dwordx4 v[102:105], v[18:19], off offset:32
	global_load_dwordx4 v[106:109], v[18:19], off offset:64
	global_load_dwordx4 v[110:113], v[18:19], off offset:96
	global_load_dwordx4 v[114:117], v[18:19], off offset:128
	global_load_dwordx4 v[118:121], v[18:19], off offset:160
	global_load_dwordx4 v[122:125], v[18:19], off offset:192
	global_load_dwordx4 v[126:129], v[18:19], off offset:224
	global_load_dwordx4 v[130:133], v[18:19], off offset:256
	global_load_dwordx4 v[134:137], v[18:19], off offset:288
	global_load_dwordx4 v[138:141], v[18:19], off offset:320
	global_load_dwordx4 v[142:145], v[18:19], off offset:352
	v_lshrrev_b32_e32 v0, 1, v16
	v_bfe_u32 v5, v16, 1, 3
	v_bitop3_b32 v0, v13, v0, 7 bitop3:0x78
	v_lshlrev_b32_e32 v209, 4, v0
	v_bitop3_b32 v0, v13, v5, 2 bitop3:0x36
	v_lshlrev_b32_e32 v210, 4, v0
	v_bitop3_b32 v0, v13, v5, 4 bitop3:0x36
	v_lshlrev_b32_e32 v213, 4, v0
	v_bitop3_b32 v0, v13, v5, 6 bitop3:0x36
	v_lshlrev_b32_e32 v214, 4, v0
	v_lshlrev_b32_e32 v0, 2, v12
	v_lshl_add_u64 v[180:181], v[10:11], 0, v[0:1]
	v_lshlrev_b32_e32 v0, 2, v8
	v_mul_u32_u24_e32 v204, 0x180, v9
	v_bfe_u32 v9, v16, 2, 2
	v_lshl_add_u64 v[178:179], v[14:15], 0, s[92:93]
	v_lshl_add_u64 v[182:183], v[6:7], 0, v[0:1]
	v_lshlrev_b32_e32 v0, 2, v4
	v_mov_b32_e32 v14, v1
	v_mov_b32_e32 v15, v1
	s_add_i32 s14, s33, 0x100
	v_lshlrev_b32_e32 v205, 10, v13
	v_lshlrev_b32_e32 v206, 8, v9
	v_lshlrev_b32_e32 v17, 1, v16
	v_lshlrev_b32_e32 v16, 3, v16
	v_lshlrev_b32_e32 v211, 6, v9
	v_lshlrev_b32_e32 v212, 2, v13
	v_lshl_add_u64 v[176:177], v[20:21], 0, s[92:93]
	v_lshl_add_u64 v[184:185], v[2:3], 0, v[0:1]
	v_mov_b32_e32 v0, v1
	v_mov_b32_e32 v2, v1
	v_mov_b32_e32 v3, v1
	v_mov_b32_e32 v4, v1
	v_mov_b32_e32 v5, v1
	v_mov_b32_e32 v6, v1
	v_mov_b32_e32 v7, v1
	v_mov_b32_e32 v8, v1
	v_mov_b32_e32 v9, v1
	v_mov_b32_e32 v10, v1
	v_mov_b32_e32 v11, v1
	v_mov_b32_e32 v12, v1
	v_mov_b32_e32 v13, v1
	v_mov_b64_e32 v[64:65], v[14:15]
	v_mov_b64_e32 v[48:49], v[14:15]
	v_mov_b64_e32 v[32:33], v[14:15]
	s_lshr_b32 s47, s14, 6
	v_and_b32_e32 v207, 32, v17
	v_and_b32_e32 v208, 24, v16
	v_mov_b64_e32 v[62:63], v[12:13]
	v_mov_b64_e32 v[60:61], v[10:11]
	v_mov_b64_e32 v[58:59], v[8:9]
	v_mov_b64_e32 v[56:57], v[6:7]
	v_mov_b64_e32 v[54:55], v[4:5]
	v_mov_b64_e32 v[52:53], v[2:3]
	v_mov_b64_e32 v[50:51], v[0:1]
	v_mov_b64_e32 v[46:47], v[12:13]
	v_mov_b64_e32 v[44:45], v[10:11]
	v_mov_b64_e32 v[42:43], v[8:9]
	v_mov_b64_e32 v[40:41], v[6:7]
	v_mov_b64_e32 v[38:39], v[4:5]
	v_mov_b64_e32 v[36:37], v[2:3]
	v_mov_b64_e32 v[34:35], v[0:1]
	v_mov_b64_e32 v[30:31], v[12:13]
	v_mov_b64_e32 v[28:29], v[10:11]
	v_mov_b64_e32 v[26:27], v[8:9]
	v_mov_b64_e32 v[24:25], v[6:7]
	v_mov_b64_e32 v[22:23], v[4:5]
	v_mov_b64_e32 v[20:21], v[2:3]
	v_mov_b64_e32 v[18:19], v[0:1]
	v_mov_b64_e32 v[16:17], v[14:15]
	s_mov_b32 s46, 2
	s_add_i32 s52, s47, -1
	s_or_b32 s53, s40, 31
	v_xor_b32_e32 v215, 64, v211
	v_xor_b32_e32 v216, 0x80, v211
	v_xor_b32_e32 v217, 0xc0, v211
	s_mov_b32 s54, 0
	v_mov_b32_e32 v218, 0
	v_mov_b32_e32 v219, 0xff800000
	s_mov_b32 s55, 63
	v_mov_b64_e32 v[14:15], v[12:13]
	v_mov_b64_e32 v[12:13], v[10:11]
	v_mov_b64_e32 v[10:11], v[8:9]
	v_mov_b64_e32 v[8:9], v[6:7]
	v_mov_b64_e32 v[6:7], v[4:5]
	v_mov_b64_e32 v[4:5], v[2:3]
	v_mov_b64_e32 v[2:3], v[0:1]
	s_mov_b32 s56, 0
	s_waitcnt vmcnt(11)
	s_waitcnt vmcnt(10)
	s_waitcnt vmcnt(9)
	s_waitcnt vmcnt(8)
	s_waitcnt vmcnt(7)
	s_waitcnt vmcnt(6)
	s_waitcnt vmcnt(5)
	s_waitcnt vmcnt(4)
	s_waitcnt vmcnt(3)
	s_waitcnt vmcnt(2)
	s_waitcnt vmcnt(1)
	s_waitcnt vmcnt(0)
	s_branch .LBB0_138

; template <int DK>
; DI void attn_pass(const AttnSrc& s, const int q0, const float sc, LAS unsigned char* lds, f32x16 (&O)[4]) {
;     ...
;     { const int rem = NT - 1 - t;
;       if (rem >= DPF - 1) asm volatile("s_waitcnt vmcnt(%0)" :: "n"((DPF - 1) * PT) : "memory");
;       else if (rem == 1) asm volatile("s_waitcnt vmcnt(%0)" :: "n"(PT) : "memory");
;       else asm volatile("s_waitcnt vmcnt(0)" ::: "memory"); }
;     __builtin_amdgcn_s_barrier();
;     asm volatile("" ::: "memory");
;     if (t + DPF < NT) issue(t + DPF, pbuf);
.LBB0_142:
	s_barrier
	s_add_i32 s14, s56, 2
	s_cmp_ge_u32 s14, s47
	s_cbranch_scc1 .Ln192_top
	s_mul_i32 s15, s46, 0xa000
	s_add_i32 s56, s15, s41
	s_mov_b32 m0, s56
	s_nop 0
	global_load_lds_dwordx4 v[184:185], off
	s_add_i32 s56, s15, s42
	s_mov_b32 m0, s56
	s_nop 0
	global_load_lds_dwordx4 v[182:183], off
	s_add_i32 s56, s15, s43
	s_mov_b32 m0, s56
	s_nop 0
	global_load_lds_dwordx4 v[180:181], off
	s_add_i32 s56, s15, s44
	s_mov_b32 m0, s56
	s_nop 0
	global_load_lds_dwordx4 v[178:179], off
	s_add_i32 s15, s15, s45
	s_mov_b32 m0, s15
	s_nop 0
	global_load_lds_dwordx4 v[176:177], off
